# k-tile-0 peel (SrcC=0, first wait counted to 16, tile-header drain removed) extended to the G2 and final-layer G5 loops
# baseline (speedup 1.0000x reference)
; #define PG8_STAGE(bufoff, gbase, voff) do { _Pragma("unroll") for (int _i = 0; _i < 2; ++_i) \
;         __builtin_amdgcn_global_load_lds((const unsigned*)((const char*)(gbase) + (voff)[_i]), (PG8_LAS unsigned*)(lds + (bufoff) + ldsw + _i * 8192), 16, 0, 0); } while (0)
; #define PG8_LDA(dst, b, h) do { _Pragma("unroll") for (int m = 0; m < 4; ++m) _Pragma("unroll") for (int k = 0; k < 2; ++k) dst[m][k] = *(const PG8_LAS bf16x8*)(lds + PG8_SA(b, h) + aoff + m * 2048 + k * 1024); } while (0)
; #define PG8_LDB(dst, b, h) do { _Pragma("unroll") for (int n = 0; n < 2; ++n) _Pragma("unroll") for (int k = 0; k < 2; ++k) dst[n][k] = *(const PG8_LAS bf16x8*)(lds + PG8_SB(b, h) + boff + n * 2048 + k * 1024); } while (0)
; #define PG8_MMA(ai, bj, At, Bt) do { __builtin_amdgcn_s_setprio(1); _Pragma("unroll") for (int m = 0; m < 4; ++m) _Pragma("unroll") for (int n = 0; n < 2; ++n) _Pragma("unroll") for (int k = 0; k < 2; ++k) \
;         acc[ai][bj][m][n] = __builtin_amdgcn_mfma_f32_16x16x32_bf16(Bt[n][k], At[m][k], acc[ai][bj][m][n], 0, 0, 0); __builtin_amdgcn_s_setprio(0); } while (0)
; #define PG8_WAIT_V(n) asm volatile("s_waitcnt vmcnt(" #n ")" ::: "memory")
; #define PG8_WAIT_L(n) asm volatile("s_waitcnt lgkmcnt(" #n ")" ::: "memory")
; #define PG8_BAR __builtin_amdgcn_s_barrier()
; template <class Epi, class Sched>
; __device__ __forceinline__ void gemm_phase(PG8_LAS unsigned char* lds, const Gemm g, const Sched& S, const Epi& E) {
;     ...
;     f32x4 acc[2][2][4][2];
; #pragma unroll
;     for (int a = 0; a < 2; ++a)
; #pragma unroll
;         for (int b = 0; b < 2; ++b)
; #pragma unroll
;             for (int m = 0; m < 4; ++m)
; #pragma unroll
;                 for (int n = 0; n < 2; ++n) acc[a][b][m][n] = (f32x4){0.f, 0.f, 0.f, 0.f};
;     ...
;         for (int t = 0; t < nt; t += 2) {
;             const bool last = (t == nt - 2);
;             const char* a1 = cA + (size_t)(t + 1) * kstep;
;             const char* a2 = last ? nA : cA + (size_t)(t + 2) * kstep; const char* b2 = last ? nB : cB + (size_t)(t + 2) * kstep;
;             const char* a3 = a2 + kstep; const char* b3 = b2 + kstep;
;             PG8_LDB(B0, 0, 0); PG8_LDB(B1, 0, 1); PG8_SCHED; PG8_LDA(At, 0, 0); PG8_STAGE(PG8_SA(1, 1), a1 + hstepA, voffA);
;             PG8_WAIT_V(8); PG8_WAIT_L(0); PG8_BAR; PG8_MMA(0, 0, At, B0); PG8_MMA(0, 1, At, B1); PG8_BAR; PG8_SCHED;
.LBB0_386:
	s_ashr_i32 s15, s14, 31
	s_lshl_b64 s[16:17], s[14:15], 18
	s_add_u32 s16, s4, s16
	s_addc_u32 s17, s5, s17
	s_and_b64 s[18:19], s[0:1], exec
	s_cselect_b32 s15, s17, s21
	s_cselect_b32 s33, s16, s20
	s_ashr_i32 s13, s12, 31
	s_lshl_b64 s[18:19], s[12:13], 18
	s_add_u32 s18, s27, s18
	s_addc_u32 s19, s28, s19
	s_and_b64 s[24:25], s[0:1], exec
	s_cselect_b32 s13, s19, s23
	s_cselect_b32 s48, s18, s22
	s_add_u32 s20, s20, 0x20080
	s_addc_u32 s21, s21, 0
	s_add_u32 s49, s22, 0x100
	v_mov_b32_e32 v2, 0
	s_addc_u32 s57, s23, 0
	s_mov_b32 s58, -2
	s_add_u32 s22, s20, 0xfffe0080
	s_addc_u32 s23, s21, -1
	s_add_i32 s59, 0, 0x10000
	s_cmp_eq_u32 s58, 4
	s_cselect_b32 s25, s15, s23
	s_cselect_b32 s24, s33, s22
	s_cselect_b32 s23, s13, s57
	s_cselect_b32 s22, s48, s49
	s_add_i32 s66, 0, 0x14000
	v_add_u32_e32 v54, s59, v250
	v_add_u32_e32 v86, s66, v250
	ds_read_b128 v[34:37], v54
	ds_read_b128 v[38:41], v54 offset:1024
	ds_read_b128 v[42:45], v54 offset:2048
	ds_read_b128 v[54:57], v54 offset:3072
	ds_read_b128 v[58:61], v86
	ds_read_b128 v[62:65], v86 offset:1024
	ds_read_b128 v[70:73], v86 offset:2048
	ds_read_b128 v[86:89], v86 offset:3072
	v_lshl_add_u64 v[186:187], s[20:21], 0, v[222:223]
	s_add_i32 m0, s29, 0xc000
	ds_read_b128 v[90:93], v246
	ds_read_b128 v[102:105], v246 offset:1024
	ds_read_b128 v[114:117], v246 offset:2048
	ds_read_b128 v[126:129], v246 offset:3072
	ds_read_b128 v[138:141], v246 offset:4096
	ds_read_b128 v[150:153], v246 offset:5120
	ds_read_b128 v[162:165], v246 offset:6144
	ds_read_b128 v[174:177], v246 offset:7168
	global_load_lds_dwordx4 v[186:187], off
	v_lshl_add_u64 v[186:187], s[20:21], 0, v[224:225]
	s_add_i32 m0, s29, 0xe000
	s_nop 0
	global_load_lds_dwordx4 v[186:187], off
	s_waitcnt vmcnt(16)
	s_waitcnt lgkmcnt(0)
	s_barrier
	s_setprio 1
	s_waitcnt lgkmcnt(0)
	v_mfma_f32_16x16x32_bf16 v[170:173], v[34:37], v[114:117], 0
	v_mfma_f32_16x16x32_bf16 v[166:169], v[42:45], v[114:117], 0
	v_mfma_f32_16x16x32_bf16 v[146:149], v[34:37], v[138:141], 0
	v_mfma_f32_16x16x32_bf16 v[142:145], v[42:45], v[138:141], 0
	v_mfma_f32_16x16x32_bf16 v[122:125], v[34:37], v[162:165], 0
	v_mfma_f32_16x16x32_bf16 v[118:121], v[42:45], v[162:165], 0
	v_mfma_f32_16x16x32_bf16 v[186:189], v[34:37], v[90:93], 0
	v_mfma_f32_16x16x32_bf16 v[190:193], v[42:45], v[90:93], 0
	v_mfma_f32_16x16x32_bf16 v[170:173], v[38:41], v[126:129], v[170:173]
	v_mfma_f32_16x16x32_bf16 v[166:169], v[54:57], v[126:129], v[166:169]
	v_mfma_f32_16x16x32_bf16 v[146:149], v[38:41], v[150:153], v[146:149]
	v_mfma_f32_16x16x32_bf16 v[142:145], v[54:57], v[150:153], v[142:145]
	v_mfma_f32_16x16x32_bf16 v[122:125], v[38:41], v[174:177], v[122:125]
	v_mfma_f32_16x16x32_bf16 v[118:121], v[54:57], v[174:177], v[118:121]
	v_mfma_f32_16x16x32_bf16 v[186:189], v[38:41], v[102:105], v[186:189]
	v_mfma_f32_16x16x32_bf16 v[190:193], v[54:57], v[102:105], v[190:193]
	s_setprio 0
	s_setprio 1
	v_mfma_f32_16x16x32_bf16 v[182:185], v[58:61], v[90:93], 0
	v_mfma_f32_16x16x32_bf16 v[90:93], v[70:73], v[90:93], 0
	v_mfma_f32_16x16x32_bf16 v[182:185], v[62:65], v[102:105], v[182:185]
	v_mfma_f32_16x16x32_bf16 v[90:93], v[86:89], v[102:105], v[90:93]
	v_mfma_f32_16x16x32_bf16 v[102:105], v[58:61], v[114:117], 0
	v_mfma_f32_16x16x32_bf16 v[114:117], v[70:73], v[114:117], 0
	v_mfma_f32_16x16x32_bf16 v[130:133], v[70:73], v[138:141], 0
	v_mfma_f32_16x16x32_bf16 v[110:113], v[58:61], v[162:165], 0
	v_mfma_f32_16x16x32_bf16 v[106:109], v[70:73], v[162:165], 0
	v_mfma_f32_16x16x32_bf16 v[102:105], v[62:65], v[126:129], v[102:105]
	v_mfma_f32_16x16x32_bf16 v[114:117], v[86:89], v[126:129], v[114:117]
	v_mfma_f32_16x16x32_bf16 v[126:129], v[58:61], v[138:141], 0
	v_mfma_f32_16x16x32_bf16 v[130:133], v[86:89], v[150:153], v[130:133]
	v_mfma_f32_16x16x32_bf16 v[110:113], v[62:65], v[174:177], v[110:113]
	v_mfma_f32_16x16x32_bf16 v[106:109], v[86:89], v[174:177], v[106:109]
	v_mfma_f32_16x16x32_bf16 v[126:129], v[62:65], v[150:153], v[126:129]
	s_setprio 0
	s_barrier
; #define PG8_STAGE(bufoff, gbase, voff) do { _Pragma("unroll") for (int _i = 0; _i < 2; ++_i) \
;         __builtin_amdgcn_global_load_lds((const unsigned*)((const char*)(gbase) + (voff)[_i]), (PG8_LAS unsigned*)(lds + (bufoff) + ldsw + _i * 8192), 16, 0, 0); } while (0)
; #define PG8_LDA(dst, b, h) do { _Pragma("unroll") for (int m = 0; m < 4; ++m) _Pragma("unroll") for (int k = 0; k < 2; ++k) dst[m][k] = *(const PG8_LAS bf16x8*)(lds + PG8_SA(b, h) + aoff + m * 2048 + k * 1024); } while (0)
; #define PG8_MMA(ai, bj, At, Bt) do { __builtin_amdgcn_s_setprio(1); _Pragma("unroll") for (int m = 0; m < 4; ++m) _Pragma("unroll") for (int n = 0; n < 2; ++n) _Pragma("unroll") for (int k = 0; k < 2; ++k) \
;         acc[ai][bj][m][n] = __builtin_amdgcn_mfma_f32_16x16x32_bf16(Bt[n][k], At[m][k], acc[ai][bj][m][n], 0, 0, 0); __builtin_amdgcn_s_setprio(0); } while (0)
; #define PG8_WAIT_V(n) asm volatile("s_waitcnt vmcnt(" #n ")" ::: "memory")
; #define PG8_WAIT_L(n) asm volatile("s_waitcnt lgkmcnt(" #n ")" ::: "memory")
; #define PG8_BAR __builtin_amdgcn_s_barrier()
; #define PG8_SCHED __builtin_amdgcn_sched_barrier(0)
; template <class Epi, class Sched>
; __device__ __forceinline__ void gemm_phase(PG8_LAS unsigned char* lds, const Gemm g, const Sched& S, const Epi& E) {
;     ...
;             PG8_LDA(At, 0, 1); PG8_STAGE(PG8_SB(0, 0), b2, voffB); PG8_STAGE(PG8_SB(0, 1), b2 + hstepB, voffB); PG8_STAGE(PG8_SA(0, 0), a2, voffA);
;             PG8_WAIT_V(8); PG8_WAIT_L(0); PG8_BAR; PG8_MMA(1, 0, At, B0); PG8_MMA(1, 1, At, B1); PG8_BAR; PG8_SCHED;
	s_add_i32 s59, s59, s26
	v_lshl_add_u64 v[210:211], s[22:23], 0, v[218:219]
	s_mov_b32 m0, s59
	ds_read_b128 v[134:137], v246 offset:16384
	ds_read_b128 v[138:141], v246 offset:17408
	ds_read_b128 v[150:153], v246 offset:18432
	ds_read_b128 v[154:157], v246 offset:19456
	ds_read_b128 v[158:161], v246 offset:20480
	ds_read_b128 v[162:165], v246 offset:21504
	ds_read_b128 v[174:177], v246 offset:22528
	ds_read_b128 v[178:181], v246 offset:23552
	global_load_lds_dwordx4 v[210:211], off
	s_add_i32 m0, s59, 0x2000
	s_add_u32 s64, s22, 0x20000
	v_lshl_add_u64 v[226:227], s[22:23], 0, v[214:215]
	s_addc_u32 s65, s23, 0
	s_add_i32 s59, s66, s26
	global_load_lds_dwordx4 v[226:227], off
	v_lshl_add_u64 v[194:195], s[64:65], 0, v[218:219]
	s_mov_b32 m0, s59
	v_lshl_add_u64 v[228:229], s[24:25], 0, v[220:221]
	global_load_lds_dwordx4 v[194:195], off
	v_lshl_add_u64 v[194:195], s[64:65], 0, v[214:215]
	s_add_i32 m0, s59, 0x2000
	v_lshl_add_u64 v[230:231], s[24:25], 0, v[216:217]
	global_load_lds_dwordx4 v[194:195], off
	s_mov_b32 m0, s29
	s_nop 0
	global_load_lds_dwordx4 v[228:229], off
	s_mov_b32 m0, s30
	s_nop 0
	global_load_lds_dwordx4 v[230:231], off
	s_waitcnt vmcnt(8)
	s_waitcnt lgkmcnt(0)
	s_barrier
	s_setprio 1
	s_waitcnt lgkmcnt(0)
	v_mfma_f32_16x16x32_bf16 v[98:101], v[34:37], v[134:137], 0
	v_mfma_f32_16x16x32_bf16 v[94:97], v[42:45], v[134:137], 0
	v_mfma_f32_16x16x32_bf16 v[74:77], v[34:37], v[150:153], 0
	v_mfma_f32_16x16x32_bf16 v[66:69], v[42:45], v[150:153], 0
	v_mfma_f32_16x16x32_bf16 v[30:33], v[34:37], v[158:161], 0
	v_mfma_f32_16x16x32_bf16 v[26:29], v[42:45], v[158:161], 0
	v_mfma_f32_16x16x32_bf16 v[14:17], v[34:37], v[174:177], 0
	v_mfma_f32_16x16x32_bf16 v[10:13], v[42:45], v[174:177], 0
	v_mfma_f32_16x16x32_bf16 v[98:101], v[38:41], v[138:141], v[98:101]
	v_mfma_f32_16x16x32_bf16 v[94:97], v[54:57], v[138:141], v[94:97]
	v_mfma_f32_16x16x32_bf16 v[74:77], v[38:41], v[154:157], v[74:77]
	v_mfma_f32_16x16x32_bf16 v[66:69], v[54:57], v[154:157], v[66:69]
	v_mfma_f32_16x16x32_bf16 v[30:33], v[38:41], v[162:165], v[30:33]
	v_mfma_f32_16x16x32_bf16 v[26:29], v[54:57], v[162:165], v[26:29]
	v_mfma_f32_16x16x32_bf16 v[14:17], v[38:41], v[178:181], v[14:17]
	v_mfma_f32_16x16x32_bf16 v[10:13], v[54:57], v[178:181], v[10:13]
	s_setprio 0
	s_setprio 1
	v_mfma_f32_16x16x32_bf16 v[46:49], v[70:73], v[150:153], 0
	v_mfma_f32_16x16x32_bf16 v[22:25], v[58:61], v[158:161], 0
	v_mfma_f32_16x16x32_bf16 v[18:21], v[70:73], v[158:161], 0
	v_mfma_f32_16x16x32_bf16 v[6:9], v[58:61], v[174:177], 0
	v_mfma_f32_16x16x32_bf16 v[2:5], v[70:73], v[174:177], 0
	v_mfma_f32_16x16x32_bf16 v[34:37], v[58:61], v[134:137], 0
	v_mfma_f32_16x16x32_bf16 v[38:41], v[70:73], v[134:137], 0
	v_mfma_f32_16x16x32_bf16 v[42:45], v[58:61], v[150:153], 0
	v_mfma_f32_16x16x32_bf16 v[46:49], v[86:89], v[154:157], v[46:49]
	v_mfma_f32_16x16x32_bf16 v[22:25], v[62:65], v[162:165], v[22:25]
	v_mfma_f32_16x16x32_bf16 v[18:21], v[86:89], v[162:165], v[18:21]
	v_mfma_f32_16x16x32_bf16 v[6:9], v[62:65], v[178:181], v[6:9]
	v_mfma_f32_16x16x32_bf16 v[2:5], v[86:89], v[178:181], v[2:5]
	v_mfma_f32_16x16x32_bf16 v[34:37], v[62:65], v[138:141], v[34:37]
	v_mfma_f32_16x16x32_bf16 v[38:41], v[86:89], v[138:141], v[38:41]
	v_mfma_f32_16x16x32_bf16 v[42:45], v[62:65], v[154:157], v[42:45]
	s_setprio 0
	s_barrier
	s_branch .Lpeel_mid_387

; #define PG8_STAGE(bufoff, gbase, voff) do { _Pragma("unroll") for (int _i = 0; _i < 2; ++_i) \
;         __builtin_amdgcn_global_load_lds((const unsigned*)((const char*)(gbase) + (voff)[_i]), (PG8_LAS unsigned*)(lds + (bufoff) + ldsw + _i * 8192), 16, 0, 0); } while (0)
; #define PG8_LDA(dst, b, h) do { _Pragma("unroll") for (int m = 0; m < 4; ++m) _Pragma("unroll") for (int k = 0; k < 2; ++k) dst[m][k] = *(const PG8_LAS bf16x8*)(lds + PG8_SA(b, h) + aoff + m * 2048 + k * 1024); } while (0)
; #define PG8_LDB(dst, b, h) do { _Pragma("unroll") for (int n = 0; n < 2; ++n) _Pragma("unroll") for (int k = 0; k < 2; ++k) dst[n][k] = *(const PG8_LAS bf16x8*)(lds + PG8_SB(b, h) + boff + n * 2048 + k * 1024); } while (0)
; #define PG8_MMA(ai, bj, At, Bt) do { __builtin_amdgcn_s_setprio(1); _Pragma("unroll") for (int m = 0; m < 4; ++m) _Pragma("unroll") for (int n = 0; n < 2; ++n) _Pragma("unroll") for (int k = 0; k < 2; ++k) \
;         acc[ai][bj][m][n] = __builtin_amdgcn_mfma_f32_16x16x32_bf16(Bt[n][k], At[m][k], acc[ai][bj][m][n], 0, 0, 0); __builtin_amdgcn_s_setprio(0); } while (0)
; #define PG8_WAIT_V(n) asm volatile("s_waitcnt vmcnt(" #n ")" ::: "memory")
; #define PG8_WAIT_L(n) asm volatile("s_waitcnt lgkmcnt(" #n ")" ::: "memory")
; #define PG8_BAR __builtin_amdgcn_s_barrier()
; #define PG8_SCHED __builtin_amdgcn_sched_barrier(0)
; template <class Epi, class Sched>
; __device__ __forceinline__ void gemm_phase(PG8_LAS unsigned char* lds, const Gemm g, const Sched& S, const Epi& E) {
;     ...
;             PG8_LDB(B0, 1, 0); PG8_LDB(B1, 1, 1); PG8_SCHED; PG8_LDA(At, 1, 0); PG8_STAGE(PG8_SA(0, 1), a2 + hstepA, voffA);
;             PG8_WAIT_V(8); PG8_WAIT_L(0); PG8_BAR; PG8_MMA(0, 0, At, B0); PG8_MMA(0, 1, At, B1); PG8_BAR; PG8_SCHED;
.Lpeel_mid_387:
	s_add_i32 s59, 0, 0x18000
	s_add_i32 s64, 0, 0x1c000
	v_add_u32_e32 v62, s59, v250
	v_add_u32_e32 v78, s64, v250
	ds_read_b128 v[50:53], v62
	ds_read_b128 v[54:57], v62 offset:1024
	ds_read_b128 v[58:61], v62 offset:2048
	ds_read_b128 v[62:65], v62 offset:3072
	ds_read_b128 v[70:73], v78
	ds_read_b128 v[86:89], v78 offset:1024
	ds_read_b128 v[138:141], v78 offset:2048
	ds_read_b128 v[150:153], v78 offset:3072
	s_add_u32 s24, s24, 0x20000
	s_addc_u32 s25, s25, 0
	s_mov_b32 m0, s31
	v_lshl_add_u64 v[158:159], s[24:25], 0, v[220:221]
	ds_read_b128 v[78:81], v246 offset:32768
	ds_read_b128 v[82:85], v246 offset:33792
	ds_read_b128 v[134:137], v246 offset:34816
	ds_read_b128 v[154:157], v246 offset:35840
	ds_read_b128 v[162:165], v246 offset:36864
	ds_read_b128 v[174:177], v246 offset:37888
	ds_read_b128 v[202:205], v246 offset:38912
	ds_read_b128 v[206:209], v246 offset:39936
	global_load_lds_dwordx4 v[158:159], off
	v_lshl_add_u64 v[158:159], s[24:25], 0, v[216:217]
	s_mov_b32 m0, s60
	s_nop 0
	global_load_lds_dwordx4 v[158:159], off
	s_waitcnt vmcnt(8)
	s_waitcnt lgkmcnt(0)
	s_barrier
	s_setprio 1
	s_waitcnt lgkmcnt(0)
	v_mfma_f32_16x16x32_bf16 v[158:161], v[50:53], v[78:81], v[186:189]
	v_mfma_f32_16x16x32_bf16 v[198:201], v[54:57], v[82:85], v[158:161]
	v_mfma_f32_16x16x32_bf16 v[158:161], v[58:61], v[78:81], v[190:193]
	v_mfma_f32_16x16x32_bf16 v[194:197], v[62:65], v[82:85], v[158:161]
	v_mfma_f32_16x16x32_bf16 v[158:161], v[50:53], v[134:137], v[170:173]
	v_mfma_f32_16x16x32_bf16 v[170:173], v[54:57], v[154:157], v[158:161]
	v_mfma_f32_16x16x32_bf16 v[158:161], v[58:61], v[134:137], v[166:169]
	v_mfma_f32_16x16x32_bf16 v[146:149], v[50:53], v[162:165], v[146:149]
	v_mfma_f32_16x16x32_bf16 v[142:145], v[58:61], v[162:165], v[142:145]
	v_mfma_f32_16x16x32_bf16 v[122:125], v[50:53], v[202:205], v[122:125]
	v_mfma_f32_16x16x32_bf16 v[118:121], v[58:61], v[202:205], v[118:121]
	v_mfma_f32_16x16x32_bf16 v[166:169], v[62:65], v[154:157], v[158:161]
	v_mfma_f32_16x16x32_bf16 v[146:149], v[54:57], v[174:177], v[146:149]
	v_mfma_f32_16x16x32_bf16 v[142:145], v[62:65], v[174:177], v[142:145]
	v_mfma_f32_16x16x32_bf16 v[122:125], v[54:57], v[206:209], v[122:125]
	v_mfma_f32_16x16x32_bf16 v[118:121], v[62:65], v[206:209], v[118:121]
	s_setprio 0
	s_setprio 1
	v_mfma_f32_16x16x32_bf16 v[158:161], v[70:73], v[78:81], v[182:185]
	v_mfma_f32_16x16x32_bf16 v[78:81], v[138:141], v[78:81], v[90:93]
	v_mfma_f32_16x16x32_bf16 v[178:181], v[150:153], v[82:85], v[78:81]
	v_mfma_f32_16x16x32_bf16 v[78:81], v[70:73], v[134:137], v[102:105]
	v_mfma_f32_16x16x32_bf16 v[182:185], v[86:89], v[82:85], v[158:161]
	v_mfma_f32_16x16x32_bf16 v[158:161], v[86:89], v[154:157], v[78:81]
	v_mfma_f32_16x16x32_bf16 v[78:81], v[138:141], v[134:137], v[114:117]
	v_mfma_f32_16x16x32_bf16 v[154:157], v[150:153], v[154:157], v[78:81]
	v_mfma_f32_16x16x32_bf16 v[78:81], v[70:73], v[162:165], v[126:129]
	v_mfma_f32_16x16x32_bf16 v[134:137], v[86:89], v[174:177], v[78:81]
	v_mfma_f32_16x16x32_bf16 v[78:81], v[138:141], v[162:165], v[130:133]
	v_mfma_f32_16x16x32_bf16 v[130:133], v[150:153], v[174:177], v[78:81]
	v_mfma_f32_16x16x32_bf16 v[78:81], v[70:73], v[202:205], v[110:113]
	v_mfma_f32_16x16x32_bf16 v[110:113], v[86:89], v[206:209], v[78:81]
	v_mfma_f32_16x16x32_bf16 v[78:81], v[138:141], v[202:205], v[106:109]
	v_mfma_f32_16x16x32_bf16 v[106:109], v[150:153], v[206:209], v[78:81]
	s_setprio 0
	s_barrier
; #define PG8_STAGE(bufoff, gbase, voff) do { _Pragma("unroll") for (int _i = 0; _i < 2; ++_i) \
;         __builtin_amdgcn_global_load_lds((const unsigned*)((const char*)(gbase) + (voff)[_i]), (PG8_LAS unsigned*)(lds + (bufoff) + ldsw + _i * 8192), 16, 0, 0); } while (0)
; #define PG8_LDA(dst, b, h) do { _Pragma("unroll") for (int m = 0; m < 4; ++m) _Pragma("unroll") for (int k = 0; k < 2; ++k) dst[m][k] = *(const PG8_LAS bf16x8*)(lds + PG8_SA(b, h) + aoff + m * 2048 + k * 1024); } while (0)
; #define PG8_MMA(ai, bj, At, Bt) do { __builtin_amdgcn_s_setprio(1); _Pragma("unroll") for (int m = 0; m < 4; ++m) _Pragma("unroll") for (int n = 0; n < 2; ++n) _Pragma("unroll") for (int k = 0; k < 2; ++k) \
;         acc[ai][bj][m][n] = __builtin_amdgcn_mfma_f32_16x16x32_bf16(Bt[n][k], At[m][k], acc[ai][bj][m][n], 0, 0, 0); __builtin_amdgcn_s_setprio(0); } while (0)
; #define PG8_WAIT_V(n) asm volatile("s_waitcnt vmcnt(" #n ")" ::: "memory")
; #define PG8_WAIT_L(n) asm volatile("s_waitcnt lgkmcnt(" #n ")" ::: "memory")
; #define PG8_BAR __builtin_amdgcn_s_barrier()
; #define PG8_SCHED __builtin_amdgcn_sched_barrier(0)
; template <class Epi, class Sched>
; __device__ __forceinline__ void gemm_phase(PG8_LAS unsigned char* lds, const Gemm g, const Sched& S, const Epi& E) {
;     ...
;             PG8_LDA(At, 1, 1); PG8_STAGE(PG8_SB(1, 0), b3, voffB); PG8_STAGE(PG8_SB(1, 1), b3 + hstepB, voffB); PG8_STAGE(PG8_SA(1, 0), a3, voffA);
;             PG8_WAIT_V(8); PG8_WAIT_L(0); PG8_BAR; PG8_MMA(1, 0, At, B0); PG8_MMA(1, 1, At, B1); PG8_BAR; PG8_SCHED;
;         }
	s_add_i32 s24, s59, s26
	v_lshl_add_u64 v[82:83], v[210:211], 0, s[78:79]
	s_mov_b32 m0, s24
	s_nop 1
	ds_read_b128 v[78:81], v246 offset:49152
	ds_read_b128 v[90:93], v246 offset:50176
	ds_read_b128 v[102:105], v246 offset:51200
	ds_read_b128 v[114:117], v246 offset:52224
	ds_read_b128 v[126:129], v246 offset:53248
	ds_read_b128 v[162:165], v246 offset:54272
	ds_read_b128 v[174:177], v246 offset:55296
	ds_read_b128 v[186:189], v246 offset:56320
	global_load_lds_dwordx4 v[82:83], off
	s_add_i32 m0, s24, 0x2000
	s_add_u32 s22, s22, 0x20080
	v_lshl_add_u64 v[82:83], v[226:227], 0, s[78:79]
	s_addc_u32 s23, s23, 0
	s_add_i32 s24, s64, s26
	global_load_lds_dwordx4 v[82:83], off
	v_lshl_add_u64 v[82:83], s[22:23], 0, v[218:219]
	s_mov_b32 m0, s24
	s_nop 0
	global_load_lds_dwordx4 v[82:83], off
	v_lshl_add_u64 v[82:83], s[22:23], 0, v[214:215]
	s_add_i32 m0, s24, 0x2000
	s_nop 0
	global_load_lds_dwordx4 v[82:83], off
	v_lshl_add_u64 v[82:83], v[228:229], 0, s[78:79]
	s_mov_b32 m0, s61
	s_nop 0
	global_load_lds_dwordx4 v[82:83], off
	v_lshl_add_u64 v[82:83], v[230:231], 0, s[78:79]
	s_mov_b32 m0, s70
	s_nop 0
	global_load_lds_dwordx4 v[82:83], off
	s_waitcnt vmcnt(8)
	s_waitcnt lgkmcnt(0)
	s_barrier
	s_setprio 1
	s_waitcnt lgkmcnt(0)
	v_mfma_f32_16x16x32_bf16 v[82:85], v[50:53], v[78:81], v[98:101]
	v_mfma_f32_16x16x32_bf16 v[98:101], v[54:57], v[90:93], v[82:85]
	v_mfma_f32_16x16x32_bf16 v[82:85], v[58:61], v[78:81], v[94:97]
	v_mfma_f32_16x16x32_bf16 v[74:77], v[50:53], v[102:105], v[74:77]
	v_mfma_f32_16x16x32_bf16 v[66:69], v[58:61], v[102:105], v[66:69]
	v_mfma_f32_16x16x32_bf16 v[30:33], v[50:53], v[126:129], v[30:33]
	v_mfma_f32_16x16x32_bf16 v[26:29], v[58:61], v[126:129], v[26:29]
	v_mfma_f32_16x16x32_bf16 v[14:17], v[50:53], v[174:177], v[14:17]
	v_mfma_f32_16x16x32_bf16 v[10:13], v[58:61], v[174:177], v[10:13]
	v_mfma_f32_16x16x32_bf16 v[94:97], v[62:65], v[90:93], v[82:85]
	v_mfma_f32_16x16x32_bf16 v[74:77], v[54:57], v[114:117], v[74:77]
	v_mfma_f32_16x16x32_bf16 v[66:69], v[62:65], v[114:117], v[66:69]
	v_mfma_f32_16x16x32_bf16 v[30:33], v[54:57], v[162:165], v[30:33]
	v_mfma_f32_16x16x32_bf16 v[26:29], v[62:65], v[162:165], v[26:29]
	v_mfma_f32_16x16x32_bf16 v[14:17], v[54:57], v[186:189], v[14:17]
	v_mfma_f32_16x16x32_bf16 v[10:13], v[62:65], v[186:189], v[10:13]
	s_setprio 0
	s_setprio 1
	v_mfma_f32_16x16x32_bf16 v[34:37], v[70:73], v[78:81], v[34:37]
	v_mfma_f32_16x16x32_bf16 v[82:85], v[86:89], v[90:93], v[34:37]
	v_mfma_f32_16x16x32_bf16 v[34:37], v[138:141], v[78:81], v[38:41]
	v_mfma_f32_16x16x32_bf16 v[78:81], v[150:153], v[90:93], v[34:37]
	v_mfma_f32_16x16x32_bf16 v[34:37], v[70:73], v[102:105], v[42:45]
	v_mfma_f32_16x16x32_bf16 v[50:53], v[86:89], v[114:117], v[34:37]
	v_mfma_f32_16x16x32_bf16 v[34:37], v[138:141], v[102:105], v[46:49]
	v_mfma_f32_16x16x32_bf16 v[22:25], v[70:73], v[126:129], v[22:25]
	v_mfma_f32_16x16x32_bf16 v[18:21], v[138:141], v[126:129], v[18:21]
	v_mfma_f32_16x16x32_bf16 v[6:9], v[70:73], v[174:177], v[6:9]
	v_mfma_f32_16x16x32_bf16 v[2:5], v[138:141], v[174:177], v[2:5]
	v_mfma_f32_16x16x32_bf16 v[46:49], v[150:153], v[114:117], v[34:37]
	v_mfma_f32_16x16x32_bf16 v[22:25], v[86:89], v[162:165], v[22:25]
	v_mfma_f32_16x16x32_bf16 v[18:21], v[150:153], v[162:165], v[18:21]
	v_mfma_f32_16x16x32_bf16 v[6:9], v[86:89], v[186:189], v[6:9]
	v_mfma_f32_16x16x32_bf16 v[2:5], v[150:153], v[186:189], v[2:5]
	s_setprio 0
	s_barrier
	s_add_i32 s58, s58, 2
	s_add_u32 s20, s20, 0x100
	s_addc_u32 s21, s21, 0
	s_add_u32 s49, s49, 0x100
	s_addc_u32 s57, s57, 0
	s_cmp_gt_u32 s58, 5
	s_cbranch_scc0 .LBB0_387
	s_and_b64 vcc, exec, s[10:11]
	s_cbranch_vccz .LBB0_390
	s_barrier

; #define PG8_STAGE(bufoff, gbase, voff) do { _Pragma("unroll") for (int _i = 0; _i < 2; ++_i) \
;         __builtin_amdgcn_global_load_lds((const unsigned*)((const char*)(gbase) + (voff)[_i]), (PG8_LAS unsigned*)(lds + (bufoff) + ldsw + _i * 8192), 16, 0, 0); } while (0)
; #define PG8_LDA(dst, b, h) do { _Pragma("unroll") for (int m = 0; m < 4; ++m) _Pragma("unroll") for (int k = 0; k < 2; ++k) dst[m][k] = *(const PG8_LAS bf16x8*)(lds + PG8_SA(b, h) + aoff + m * 2048 + k * 1024); } while (0)
; #define PG8_LDB(dst, b, h) do { _Pragma("unroll") for (int n = 0; n < 2; ++n) _Pragma("unroll") for (int k = 0; k < 2; ++k) dst[n][k] = *(const PG8_LAS bf16x8*)(lds + PG8_SB(b, h) + boff + n * 2048 + k * 1024); } while (0)
; #define PG8_WAIT_V(n) asm volatile("s_waitcnt vmcnt(" #n ")" ::: "memory")
; #define PG8_WAIT_L(n) asm volatile("s_waitcnt lgkmcnt(" #n ")" ::: "memory")
; #define PG8_BAR __builtin_amdgcn_s_barrier()
; #define PG8_SCHED __builtin_amdgcn_sched_barrier(0)
; template <class Epi, class Sched>
; __device__ __forceinline__ void gemm_phase(PG8_LAS unsigned char* lds, const Gemm g, const Sched& S, const Epi& E) {
;     ...
;     f32x4 acc[2][2][4][2];
; #pragma unroll
;     for (int a = 0; a < 2; ++a)
; #pragma unroll
;         for (int b = 0; b < 2; ++b)
; #pragma unroll
;             for (int m = 0; m < 4; ++m)
; #pragma unroll
;                 for (int n = 0; n < 2; ++n) acc[a][b][m][n] = (f32x4){0.f, 0.f, 0.f, 0.f};
;     ...
;         for (int t = 0; t < nt; t += 2) {
;             const bool last = (t == nt - 2);
;             const char* a1 = cA + (size_t)(t + 1) * kstep;
;             const char* a2 = last ? nA : cA + (size_t)(t + 2) * kstep; const char* b2 = last ? nB : cB + (size_t)(t + 2) * kstep;
;             const char* a3 = a2 + kstep; const char* b3 = b2 + kstep;
;             PG8_LDB(B0, 0, 0); PG8_LDB(B1, 0, 1); PG8_SCHED; PG8_LDA(At, 0, 0); PG8_STAGE(PG8_SA(1, 1), a1 + hstepA, voffA);
;             PG8_WAIT_V(8); PG8_WAIT_L(0); PG8_BAR; PG8_MMA(0, 0, At, B0); PG8_MMA(0, 1, At, B1); PG8_BAR; PG8_SCHED;
;             PG8_LDA(At, 0, 1); PG8_STAGE(PG8_SB(0, 0), b2, voffB); PG8_STAGE(PG8_SB(0, 1), b2 + hstepB, voffB); PG8_STAGE(PG8_SA(0, 0), a2, voffA);
;             PG8_WAIT_V(8); PG8_WAIT_L(0); PG8_BAR; PG8_MMA(1, 0, At, B0); PG8_MMA(1, 1, At, B1); PG8_BAR; PG8_SCHED;
.LBB0_732:
	s_add_u32 s19, s24, 0x100
	v_mov_b32_e32 v2, 0
	s_addc_u32 s21, s25, 0
	s_mov_b32 s33, -2
	s_add_u32 s0, s22, 0x100
	s_addc_u32 s1, s23, 0
	s_add_i32 s46, 0, 0x10000
	s_cmp_eq_u32 s33, 40
	s_cselect_b32 s27, s15, s1
	s_cselect_b32 s26, s14, s0
	s_cselect_b32 s25, s17, s21
	s_cselect_b32 s24, s16, s19
	s_add_i32 s47, 0, 0x14000
	v_add_u32_e32 v30, s46, v1
	v_add_u32_e32 v158, s47, v1
	ds_read_b128 v[18:21], v30
	ds_read_b128 v[22:25], v30 offset:1024
	ds_read_b128 v[26:29], v30 offset:2048
	ds_read_b128 v[30:33], v30 offset:3072
	ds_read_b128 v[138:141], v158
	ds_read_b128 v[150:153], v158 offset:1024
	ds_read_b128 v[154:157], v158 offset:2048
	ds_read_b128 v[158:161], v158 offset:3072
	v_lshl_add_u64 v[212:213], s[22:23], 0, v[204:205]
	s_add_i32 m0, s29, 0xc000
	ds_read_b128 v[162:165], v235
	ds_read_b128 v[166:169], v235 offset:1024
	ds_read_b128 v[170:173], v235 offset:2048
	ds_read_b128 v[174:177], v235 offset:3072
	ds_read_b128 v[208:211], v235 offset:4096
	ds_read_b128 v[214:217], v235 offset:5120
	ds_read_b128 v[218:221], v235 offset:6144
	ds_read_b128 v[222:225], v235 offset:7168
	global_load_lds_dwordx4 v[212:213], off
	v_lshl_add_u64 v[212:213], s[22:23], 0, v[206:207]
	s_add_i32 m0, s29, 0xe000
	s_nop 0
	global_load_lds_dwordx4 v[212:213], off
	s_waitcnt vmcnt(16)
	s_waitcnt lgkmcnt(0)
	s_barrier
	s_setprio 1
	s_waitcnt lgkmcnt(0)
	v_mfma_f32_16x16x32_bf16 v[146:149], v[18:21], v[162:165], 0
	v_mfma_f32_16x16x32_bf16 v[142:145], v[26:29], v[162:165], 0
	v_mfma_f32_16x16x32_bf16 v[126:129], v[18:21], v[170:173], 0
	v_mfma_f32_16x16x32_bf16 v[122:125], v[26:29], v[170:173], 0
	v_mfma_f32_16x16x32_bf16 v[110:113], v[18:21], v[208:211], 0
	v_mfma_f32_16x16x32_bf16 v[106:109], v[26:29], v[208:211], 0
	v_mfma_f32_16x16x32_bf16 v[94:97], v[18:21], v[218:221], 0
	v_mfma_f32_16x16x32_bf16 v[90:93], v[26:29], v[218:221], 0
	v_mfma_f32_16x16x32_bf16 v[146:149], v[22:25], v[166:169], v[146:149]
	v_mfma_f32_16x16x32_bf16 v[142:145], v[30:33], v[166:169], v[142:145]
	v_mfma_f32_16x16x32_bf16 v[126:129], v[22:25], v[174:177], v[126:129]
	v_mfma_f32_16x16x32_bf16 v[122:125], v[30:33], v[174:177], v[122:125]
	v_mfma_f32_16x16x32_bf16 v[110:113], v[22:25], v[214:217], v[110:113]
	v_mfma_f32_16x16x32_bf16 v[106:109], v[30:33], v[214:217], v[106:109]
	v_mfma_f32_16x16x32_bf16 v[94:97], v[22:25], v[222:225], v[94:97]
	v_mfma_f32_16x16x32_bf16 v[90:93], v[30:33], v[222:225], v[90:93]
	s_setprio 0
	s_setprio 1
	v_mfma_f32_16x16x32_bf16 v[134:137], v[138:141], v[162:165], 0
	v_mfma_f32_16x16x32_bf16 v[130:133], v[154:157], v[162:165], 0
	v_mfma_f32_16x16x32_bf16 v[118:121], v[138:141], v[170:173], 0
	v_mfma_f32_16x16x32_bf16 v[114:117], v[154:157], v[170:173], 0
	v_mfma_f32_16x16x32_bf16 v[102:105], v[138:141], v[208:211], 0
	v_mfma_f32_16x16x32_bf16 v[98:101], v[154:157], v[208:211], 0
	v_mfma_f32_16x16x32_bf16 v[86:89], v[138:141], v[218:221], 0
	v_mfma_f32_16x16x32_bf16 v[82:85], v[154:157], v[218:221], 0
	v_mfma_f32_16x16x32_bf16 v[134:137], v[150:153], v[166:169], v[134:137]
	v_mfma_f32_16x16x32_bf16 v[130:133], v[158:161], v[166:169], v[130:133]
	v_mfma_f32_16x16x32_bf16 v[118:121], v[150:153], v[174:177], v[118:121]
	v_mfma_f32_16x16x32_bf16 v[114:117], v[158:161], v[174:177], v[114:117]
	v_mfma_f32_16x16x32_bf16 v[102:105], v[150:153], v[214:217], v[102:105]
	v_mfma_f32_16x16x32_bf16 v[98:101], v[158:161], v[214:217], v[98:101]
	v_mfma_f32_16x16x32_bf16 v[86:89], v[150:153], v[222:225], v[86:89]
	v_mfma_f32_16x16x32_bf16 v[82:85], v[158:161], v[222:225], v[82:85]
	s_setprio 0
	s_barrier
	s_add_i32 s22, s46, s28
	v_lshl_add_u64 v[212:213], s[24:25], 0, v[182:183]
	s_mov_b32 m0, s22
	ds_read_b128 v[162:165], v235 offset:16384
	ds_read_b128 v[166:169], v235 offset:17408
	ds_read_b128 v[170:173], v235 offset:18432
	ds_read_b128 v[174:177], v235 offset:19456
	ds_read_b128 v[208:211], v235 offset:20480
	ds_read_b128 v[214:217], v235 offset:21504
	ds_read_b128 v[218:221], v235 offset:22528
	ds_read_b128 v[222:225], v235 offset:23552
	global_load_lds_dwordx4 v[212:213], off
	s_add_i32 m0, s22, 0x2000
	s_add_u32 s22, s24, 0xb0000
	v_lshl_add_u64 v[226:227], s[24:25], 0, v[178:179]
	s_addc_u32 s23, s25, 0
	s_add_i32 s46, s47, s28
	global_load_lds_dwordx4 v[226:227], off
	v_lshl_add_u64 v[238:239], s[22:23], 0, v[182:183]
	s_mov_b32 m0, s46
	v_lshl_add_u64 v[240:241], s[26:27], 0, v[180:181]
	global_load_lds_dwordx4 v[238:239], off
	v_lshl_add_u64 v[238:239], s[22:23], 0, v[178:179]
	s_add_i32 m0, s46, 0x2000
	s_nop 0
	global_load_lds_dwordx4 v[238:239], off
	v_lshl_add_u64 v[238:239], s[26:27], 0, v[184:185]
	s_mov_b32 m0, s29
	s_nop 0
	global_load_lds_dwordx4 v[238:239], off
	s_mov_b32 m0, s30
	s_nop 0
	global_load_lds_dwordx4 v[240:241], off
	s_waitcnt vmcnt(8)
	s_waitcnt lgkmcnt(0)
	s_barrier
	s_setprio 1
	s_waitcnt lgkmcnt(0)
	v_mfma_f32_16x16x32_bf16 v[78:81], v[18:21], v[162:165], 0
	v_mfma_f32_16x16x32_bf16 v[74:77], v[26:29], v[162:165], 0
	v_mfma_f32_16x16x32_bf16 v[62:65], v[18:21], v[170:173], 0
	v_mfma_f32_16x16x32_bf16 v[58:61], v[26:29], v[170:173], 0
	v_mfma_f32_16x16x32_bf16 v[46:49], v[18:21], v[208:211], 0
	v_mfma_f32_16x16x32_bf16 v[42:45], v[26:29], v[208:211], 0
	v_mfma_f32_16x16x32_bf16 v[14:17], v[18:21], v[218:221], 0
	v_mfma_f32_16x16x32_bf16 v[10:13], v[26:29], v[218:221], 0
	v_mfma_f32_16x16x32_bf16 v[78:81], v[22:25], v[166:169], v[78:81]
	v_mfma_f32_16x16x32_bf16 v[74:77], v[30:33], v[166:169], v[74:77]
	v_mfma_f32_16x16x32_bf16 v[62:65], v[22:25], v[174:177], v[62:65]
	v_mfma_f32_16x16x32_bf16 v[58:61], v[30:33], v[174:177], v[58:61]
	v_mfma_f32_16x16x32_bf16 v[46:49], v[22:25], v[214:217], v[46:49]
	v_mfma_f32_16x16x32_bf16 v[42:45], v[30:33], v[214:217], v[42:45]
	v_mfma_f32_16x16x32_bf16 v[14:17], v[22:25], v[222:225], v[14:17]
	v_mfma_f32_16x16x32_bf16 v[10:13], v[30:33], v[222:225], v[10:13]
	s_setprio 0
	s_setprio 1
	v_mfma_f32_16x16x32_bf16 v[38:41], v[138:141], v[208:211], 0
	v_mfma_f32_16x16x32_bf16 v[34:37], v[154:157], v[208:211], 0
	v_mfma_f32_16x16x32_bf16 v[6:9], v[138:141], v[218:221], 0
	v_mfma_f32_16x16x32_bf16 v[2:5], v[154:157], v[218:221], 0
	v_mfma_f32_16x16x32_bf16 v[18:21], v[138:141], v[162:165], 0
	v_mfma_f32_16x16x32_bf16 v[22:25], v[154:157], v[162:165], 0
	v_mfma_f32_16x16x32_bf16 v[26:29], v[138:141], v[170:173], 0
	v_mfma_f32_16x16x32_bf16 v[30:33], v[154:157], v[170:173], 0
	v_mfma_f32_16x16x32_bf16 v[38:41], v[150:153], v[214:217], v[38:41]
	v_mfma_f32_16x16x32_bf16 v[34:37], v[158:161], v[214:217], v[34:37]
	v_mfma_f32_16x16x32_bf16 v[6:9], v[150:153], v[222:225], v[6:9]
	v_mfma_f32_16x16x32_bf16 v[2:5], v[158:161], v[222:225], v[2:5]
	v_mfma_f32_16x16x32_bf16 v[18:21], v[150:153], v[166:169], v[18:21]
	v_mfma_f32_16x16x32_bf16 v[22:25], v[158:161], v[166:169], v[22:25]
	v_mfma_f32_16x16x32_bf16 v[26:29], v[150:153], v[174:177], v[26:29]
	v_mfma_f32_16x16x32_bf16 v[30:33], v[158:161], v[174:177], v[30:33]
	s_setprio 0
	s_barrier
	s_branch .Lpeel_mid_733

; #define PG8_STAGE(bufoff, gbase, voff) do { _Pragma("unroll") for (int _i = 0; _i < 2; ++_i) \
;         __builtin_amdgcn_global_load_lds((const unsigned*)((const char*)(gbase) + (voff)[_i]), (PG8_LAS unsigned*)(lds + (bufoff) + ldsw + _i * 8192), 16, 0, 0); } while (0)
; #define PG8_LDA(dst, b, h) do { _Pragma("unroll") for (int m = 0; m < 4; ++m) _Pragma("unroll") for (int k = 0; k < 2; ++k) dst[m][k] = *(const PG8_LAS bf16x8*)(lds + PG8_SA(b, h) + aoff + m * 2048 + k * 1024); } while (0)
; #define PG8_LDB(dst, b, h) do { _Pragma("unroll") for (int n = 0; n < 2; ++n) _Pragma("unroll") for (int k = 0; k < 2; ++k) dst[n][k] = *(const PG8_LAS bf16x8*)(lds + PG8_SB(b, h) + boff + n * 2048 + k * 1024); } while (0)
; #define PG8_MMA(ai, bj, At, Bt) do { __builtin_amdgcn_s_setprio(1); _Pragma("unroll") for (int m = 0; m < 4; ++m) _Pragma("unroll") for (int n = 0; n < 2; ++n) _Pragma("unroll") for (int k = 0; k < 2; ++k) \
;         acc[ai][bj][m][n] = __builtin_amdgcn_mfma_f32_16x16x32_bf16(Bt[n][k], At[m][k], acc[ai][bj][m][n], 0, 0, 0); __builtin_amdgcn_s_setprio(0); } while (0)
; #define PG8_WAIT_V(n) asm volatile("s_waitcnt vmcnt(" #n ")" ::: "memory")
; #define PG8_WAIT_L(n) asm volatile("s_waitcnt lgkmcnt(" #n ")" ::: "memory")
; #define PG8_BAR __builtin_amdgcn_s_barrier()
; #define PG8_SCHED __builtin_amdgcn_sched_barrier(0)
; template <class Epi, class Sched>
; __device__ __forceinline__ void gemm_phase(PG8_LAS unsigned char* lds, const Gemm g, const Sched& S, const Epi& E) {
;     ...
;             PG8_LDB(B0, 1, 0); PG8_LDB(B1, 1, 1); PG8_SCHED; PG8_LDA(At, 1, 0); PG8_STAGE(PG8_SA(0, 1), a2 + hstepA, voffA);
;             PG8_WAIT_V(8); PG8_WAIT_L(0); PG8_BAR; PG8_MMA(0, 0, At, B0); PG8_MMA(0, 1, At, B1); PG8_BAR; PG8_SCHED;
.Lpeel_mid_733:
	s_add_i32 s46, 0, 0x18000
	s_add_i32 s47, 0, 0x1c000
	v_add_u32_e32 v70, s46, v1
	v_add_u32_e32 v158, s47, v1
	ds_read_b128 v[50:53], v70
	ds_read_b128 v[54:57], v70 offset:1024
	ds_read_b128 v[66:69], v70 offset:2048
	ds_read_b128 v[70:73], v70 offset:3072
	ds_read_b128 v[138:141], v158
	ds_read_b128 v[150:153], v158 offset:1024
	ds_read_b128 v[154:157], v158 offset:2048
	ds_read_b128 v[158:161], v158 offset:3072
	s_add_u32 s22, s26, 0xb0000
	s_addc_u32 s23, s27, 0
	s_mov_b32 m0, s31
	v_lshl_add_u64 v[242:243], s[22:23], 0, v[184:185]
	ds_read_b128 v[162:165], v235 offset:32768
	ds_read_b128 v[166:169], v235 offset:33792
	ds_read_b128 v[170:173], v235 offset:34816
	ds_read_b128 v[174:177], v235 offset:35840
	ds_read_b128 v[208:211], v235 offset:36864
	ds_read_b128 v[214:217], v235 offset:37888
	ds_read_b128 v[218:221], v235 offset:38912
	ds_read_b128 v[222:225], v235 offset:39936
	global_load_lds_dwordx4 v[242:243], off
	v_lshl_add_u64 v[242:243], s[22:23], 0, v[180:181]
	s_mov_b32 m0, s60
	s_nop 0
	global_load_lds_dwordx4 v[242:243], off
	s_waitcnt vmcnt(8)
	s_waitcnt lgkmcnt(0)
	s_barrier
	s_setprio 1
	s_waitcnt lgkmcnt(0)
	v_mfma_f32_16x16x32_bf16 v[146:149], v[50:53], v[162:165], v[146:149]
	v_mfma_f32_16x16x32_bf16 v[142:145], v[66:69], v[162:165], v[142:145]
	v_mfma_f32_16x16x32_bf16 v[126:129], v[50:53], v[170:173], v[126:129]
	v_mfma_f32_16x16x32_bf16 v[122:125], v[66:69], v[170:173], v[122:125]
	v_mfma_f32_16x16x32_bf16 v[110:113], v[50:53], v[208:211], v[110:113]
	v_mfma_f32_16x16x32_bf16 v[106:109], v[66:69], v[208:211], v[106:109]
	v_mfma_f32_16x16x32_bf16 v[94:97], v[50:53], v[218:221], v[94:97]
	v_mfma_f32_16x16x32_bf16 v[90:93], v[66:69], v[218:221], v[90:93]
	v_mfma_f32_16x16x32_bf16 v[146:149], v[54:57], v[166:169], v[146:149]
	v_mfma_f32_16x16x32_bf16 v[142:145], v[70:73], v[166:169], v[142:145]
	v_mfma_f32_16x16x32_bf16 v[126:129], v[54:57], v[174:177], v[126:129]
	v_mfma_f32_16x16x32_bf16 v[122:125], v[70:73], v[174:177], v[122:125]
	v_mfma_f32_16x16x32_bf16 v[110:113], v[54:57], v[214:217], v[110:113]
	v_mfma_f32_16x16x32_bf16 v[106:109], v[70:73], v[214:217], v[106:109]
	v_mfma_f32_16x16x32_bf16 v[94:97], v[54:57], v[222:225], v[94:97]
	v_mfma_f32_16x16x32_bf16 v[90:93], v[70:73], v[222:225], v[90:93]
	s_setprio 0
	s_setprio 1
	v_mfma_f32_16x16x32_bf16 v[134:137], v[138:141], v[162:165], v[134:137]
	v_mfma_f32_16x16x32_bf16 v[130:133], v[154:157], v[162:165], v[130:133]
	v_mfma_f32_16x16x32_bf16 v[118:121], v[138:141], v[170:173], v[118:121]
	v_mfma_f32_16x16x32_bf16 v[114:117], v[154:157], v[170:173], v[114:117]
	v_mfma_f32_16x16x32_bf16 v[102:105], v[138:141], v[208:211], v[102:105]
	v_mfma_f32_16x16x32_bf16 v[98:101], v[154:157], v[208:211], v[98:101]
	v_mfma_f32_16x16x32_bf16 v[86:89], v[138:141], v[218:221], v[86:89]
	v_mfma_f32_16x16x32_bf16 v[82:85], v[154:157], v[218:221], v[82:85]
	v_mfma_f32_16x16x32_bf16 v[134:137], v[150:153], v[166:169], v[134:137]
	v_mfma_f32_16x16x32_bf16 v[130:133], v[158:161], v[166:169], v[130:133]
	v_mfma_f32_16x16x32_bf16 v[118:121], v[150:153], v[174:177], v[118:121]
	v_mfma_f32_16x16x32_bf16 v[114:117], v[158:161], v[174:177], v[114:117]
	v_mfma_f32_16x16x32_bf16 v[102:105], v[150:153], v[214:217], v[102:105]
	v_mfma_f32_16x16x32_bf16 v[98:101], v[158:161], v[214:217], v[98:101]
	v_mfma_f32_16x16x32_bf16 v[86:89], v[150:153], v[222:225], v[86:89]
	v_mfma_f32_16x16x32_bf16 v[82:85], v[158:161], v[222:225], v[82:85]
	s_setprio 0
	s_barrier
; #define PG8_STAGE(bufoff, gbase, voff) do { _Pragma("unroll") for (int _i = 0; _i < 2; ++_i) \
;         __builtin_amdgcn_global_load_lds((const unsigned*)((const char*)(gbase) + (voff)[_i]), (PG8_LAS unsigned*)(lds + (bufoff) + ldsw + _i * 8192), 16, 0, 0); } while (0)
; #define PG8_LDA(dst, b, h) do { _Pragma("unroll") for (int m = 0; m < 4; ++m) _Pragma("unroll") for (int k = 0; k < 2; ++k) dst[m][k] = *(const PG8_LAS bf16x8*)(lds + PG8_SA(b, h) + aoff + m * 2048 + k * 1024); } while (0)
; #define PG8_MMA(ai, bj, At, Bt) do { __builtin_amdgcn_s_setprio(1); _Pragma("unroll") for (int m = 0; m < 4; ++m) _Pragma("unroll") for (int n = 0; n < 2; ++n) _Pragma("unroll") for (int k = 0; k < 2; ++k) \
;         acc[ai][bj][m][n] = __builtin_amdgcn_mfma_f32_16x16x32_bf16(Bt[n][k], At[m][k], acc[ai][bj][m][n], 0, 0, 0); __builtin_amdgcn_s_setprio(0); } while (0)
; #define PG8_WAIT_V(n) asm volatile("s_waitcnt vmcnt(" #n ")" ::: "memory")
; #define PG8_WAIT_L(n) asm volatile("s_waitcnt lgkmcnt(" #n ")" ::: "memory")
; #define PG8_BAR __builtin_amdgcn_s_barrier()
; #define PG8_SCHED __builtin_amdgcn_sched_barrier(0)
; template <class Epi, class Sched>
; __device__ __forceinline__ void gemm_phase(PG8_LAS unsigned char* lds, const Gemm g, const Sched& S, const Epi& E) {
;     ...
;             PG8_LDA(At, 1, 1); PG8_STAGE(PG8_SB(1, 0), b3, voffB); PG8_STAGE(PG8_SB(1, 1), b3 + hstepB, voffB); PG8_STAGE(PG8_SA(1, 0), a3, voffA);
;             PG8_WAIT_V(8); PG8_WAIT_L(0); PG8_BAR; PG8_MMA(1, 0, At, B0); PG8_MMA(1, 1, At, B1); PG8_BAR; PG8_SCHED;
;         }
	s_add_i32 s22, s46, s28
	v_lshl_add_u64 v[212:213], v[212:213], 0, s[78:79]
	s_mov_b32 m0, s22
	ds_read_b128 v[162:165], v235 offset:49152
	ds_read_b128 v[166:169], v235 offset:50176
	ds_read_b128 v[170:173], v235 offset:51200
	ds_read_b128 v[174:177], v235 offset:52224
	ds_read_b128 v[208:211], v235 offset:53248
	ds_read_b128 v[214:217], v235 offset:54272
	ds_read_b128 v[218:221], v235 offset:55296
	ds_read_b128 v[222:225], v235 offset:56320
	global_load_lds_dwordx4 v[212:213], off
	s_add_i32 m0, s22, 0x2000
	s_add_u32 s22, s24, 0xb0080
	v_lshl_add_u64 v[212:213], v[226:227], 0, s[78:79]
	s_addc_u32 s23, s25, 0
	s_add_i32 s24, s47, s28
	global_load_lds_dwordx4 v[212:213], off
	v_lshl_add_u64 v[212:213], s[22:23], 0, v[182:183]
	s_mov_b32 m0, s24
	s_nop 0
	global_load_lds_dwordx4 v[212:213], off
	v_lshl_add_u64 v[212:213], s[22:23], 0, v[178:179]
	s_add_i32 m0, s24, 0x2000
	s_nop 0
	global_load_lds_dwordx4 v[212:213], off
	v_lshl_add_u64 v[212:213], v[238:239], 0, s[78:79]
	s_mov_b32 m0, s61
	s_nop 0
	global_load_lds_dwordx4 v[212:213], off
	v_lshl_add_u64 v[212:213], v[240:241], 0, s[78:79]
	s_mov_b32 m0, s70
	s_nop 0
	global_load_lds_dwordx4 v[212:213], off
	s_waitcnt vmcnt(8)
	s_waitcnt lgkmcnt(0)
	s_barrier
	s_setprio 1
	s_waitcnt lgkmcnt(0)
	v_mfma_f32_16x16x32_bf16 v[78:81], v[50:53], v[162:165], v[78:81]
	v_mfma_f32_16x16x32_bf16 v[74:77], v[66:69], v[162:165], v[74:77]
	v_mfma_f32_16x16x32_bf16 v[62:65], v[50:53], v[170:173], v[62:65]
	v_mfma_f32_16x16x32_bf16 v[58:61], v[66:69], v[170:173], v[58:61]
	v_mfma_f32_16x16x32_bf16 v[46:49], v[50:53], v[208:211], v[46:49]
	v_mfma_f32_16x16x32_bf16 v[42:45], v[66:69], v[208:211], v[42:45]
	v_mfma_f32_16x16x32_bf16 v[14:17], v[50:53], v[218:221], v[14:17]
	v_mfma_f32_16x16x32_bf16 v[10:13], v[66:69], v[218:221], v[10:13]
	v_mfma_f32_16x16x32_bf16 v[78:81], v[54:57], v[166:169], v[78:81]
	v_mfma_f32_16x16x32_bf16 v[74:77], v[70:73], v[166:169], v[74:77]
	v_mfma_f32_16x16x32_bf16 v[62:65], v[54:57], v[174:177], v[62:65]
	v_mfma_f32_16x16x32_bf16 v[58:61], v[70:73], v[174:177], v[58:61]
	v_mfma_f32_16x16x32_bf16 v[46:49], v[54:57], v[214:217], v[46:49]
	v_mfma_f32_16x16x32_bf16 v[42:45], v[70:73], v[214:217], v[42:45]
	v_mfma_f32_16x16x32_bf16 v[14:17], v[54:57], v[222:225], v[14:17]
	v_mfma_f32_16x16x32_bf16 v[10:13], v[70:73], v[222:225], v[10:13]
	s_setprio 0
	s_setprio 1
	v_mfma_f32_16x16x32_bf16 v[18:21], v[138:141], v[162:165], v[18:21]
	v_mfma_f32_16x16x32_bf16 v[70:73], v[150:153], v[166:169], v[18:21]
	v_mfma_f32_16x16x32_bf16 v[18:21], v[154:157], v[162:165], v[22:25]
	v_mfma_f32_16x16x32_bf16 v[66:69], v[158:161], v[166:169], v[18:21]
	v_mfma_f32_16x16x32_bf16 v[18:21], v[138:141], v[170:173], v[26:29]
	v_mfma_f32_16x16x32_bf16 v[54:57], v[150:153], v[174:177], v[18:21]
	v_mfma_f32_16x16x32_bf16 v[18:21], v[154:157], v[170:173], v[30:33]
	v_mfma_f32_16x16x32_bf16 v[50:53], v[158:161], v[174:177], v[18:21]
	v_mfma_f32_16x16x32_bf16 v[18:21], v[138:141], v[208:211], v[38:41]
	v_mfma_f32_16x16x32_bf16 v[38:41], v[150:153], v[214:217], v[18:21]
	v_mfma_f32_16x16x32_bf16 v[18:21], v[154:157], v[208:211], v[34:37]
	v_mfma_f32_16x16x32_bf16 v[6:9], v[138:141], v[218:221], v[6:9]
	v_mfma_f32_16x16x32_bf16 v[2:5], v[154:157], v[218:221], v[2:5]
	v_mfma_f32_16x16x32_bf16 v[34:37], v[158:161], v[214:217], v[18:21]
	v_mfma_f32_16x16x32_bf16 v[6:9], v[150:153], v[222:225], v[6:9]
	v_mfma_f32_16x16x32_bf16 v[2:5], v[158:161], v[222:225], v[2:5]
	s_setprio 0
	s_barrier
	s_add_i32 s33, s33, 2
	s_add_u32 s19, s19, 0x100
	s_addc_u32 s21, s21, 0
	s_cmp_gt_u32 s33, 41
	s_mov_b64 s[22:23], s[0:1]
	s_cbranch_scc0 .LBB0_733
	s_and_b64 vcc, exec, s[12:13]
	s_cbranch_vccz .LBB0_736
	s_barrier
